# P3: the unit's four fp8-state loads issued at the very top of the unit (before the staging writes and their barrier) instead of after them
# speedup vs baseline: 1.0020x; 1.0020x over previous
; #define LAS __attribute__((address_space(3)))
; __device__ __forceinline__ f32x4 mfma16(bf16x8 a, bf16x8 b, f32x4 c) { return __builtin_amdgcn_mfma_f32_16x16x32_bf16(a, b, c, 0, 0, 0); }
; #define LBAR() asm volatile("s_waitcnt lgkmcnt(0)\n\ts_barrier" ::: "memory")
; #define OPQ_ALL() do { asm volatile("" : "+v"(g), "+v"(l15), "+v"(q4), "+v"(p)); } while (0)
; __device__ __forceinline__ void ret_phase(const Params& P, LAS unsigned char* lds, int tid, int lane, int wave, int bid, int G) {
;     ...
;         const int gc = u >> 2, h = u & 3; const size_t tokc = (size_t)gc * 128;
;         const float lgf2 = -__expf(P.dec_f[h]) * LOG2E, lgb2 = -__expf(P.dec_b[h]) * LOG2E;
; #pragma unroll
;         for (int i = 0; i < 4; ++i) { const int idx = tid + 512 * i; const unsigned d = off256(idx >> 4, idx & 15);
;             *(LAS u32x4*)(Qt + d) = rq[i]; *(LAS u32x4*)(Kt + d) = rk[i]; *(LAS u32x4*)(Vt + d) = rv[i]; }
;         LBAR();
;         const bf16_t* Sf = ST + ((size_t)(gc * 4 + h) * 2 + 0) * 16384; const bf16_t* Sb = Sf + 16384;
;         u32x4 rsf[2], rsb[2];
; #pragma unroll
;         for (int j = 0; j < 2; ++j) { const int idx = tid + 512 * j; rsf[j] = *(const u32x4*)((const unsigned char*)Sf + 16 * idx); rsb[j] = *(const u32x4*)((const unsigned char*)Sb + 16 * idx); }
;         OPQ_ALL();
;         bf16x8 qf[4];
; #pragma unroll
;         for (int ks = 0; ks < 4; ++ks) qf[ks] = *(const LAS bf16x8*)(Qt + off256(w16 + l15, 4 * ks + g));
;         {
;             const int n = w16 + l15;
;             f32x4 sa[8];
; #pragma unroll
;             for (int mt = 0; mt < 8; ++mt) {
;                 f32x4 a = (f32x4){0.f, 0.f, 0.f, 0.f};
; #pragma unroll
;                 for (int ks = 0; ks < 4; ++ks) a = mfma16(*(const LAS bf16x8*)(Kt + off256(16 * mt + l15, 4 * ks + g)), qf[ks], a);
;                 sa[mt] = a; }
.Lp3_common:
	s_ashr_i32 s27, s26, 31
	s_lshl_b64 s[0:1], s[26:27], 16
	s_add_u32 s0, s44, s0
	s_addc_u32 s1, s45, s1
	v_lshl_add_u64 v[254:255], s[0:1], 0, v[116:117]
	global_load_dwordx4 v[68:71], v[254:255], off
	v_add_co_u32_e32 v52, vcc, s47, v254
	v_addc_co_u32_e32 v53, vcc, 0, v255, vcc
	global_load_dwordx4 v[76:79], v[52:53], off
	v_add_co_u32_e32 v52, vcc, s49, v254
	v_addc_co_u32_e32 v53, vcc, 0, v255, vcc
	global_load_dwordx4 v[84:87], v[52:53], off
	v_add_co_u32_e32 v52, vcc, s50, v254
	v_addc_co_u32_e32 v53, vcc, 0, v255, vcc
	global_load_dwordx4 v[92:95], v[52:53], off
	ds_write_b128 v50, v[6:9]
	ds_write_b128 v50, v[2:5] offset:32768
	ds_write_b128 v51, v[10:13]
	v_add_u32_e32 v51, 0, v109
	s_ashr_i32 s27, s26, 31
	s_ashr_i32 s40, s26, 2
	ds_write_b128 v51, v[14:17]
	ds_write_b128 v51, v[22:25] offset:32768
	v_add_u32_e32 v51, s48, v109
	s_lshl_b64 s[0:1], s[26:27], 16
	ds_write_b128 v51, v[18:21]
	ds_write_b128 v50, v[30:33] offset:16384
	ds_write_b128 v50, v[26:29] offset:49152
	ds_write_b128 v127, v[34:37]
	v_add_u32_e32 v50, 0, v111
	s_add_u32 s0, s44, s0
	ds_write_b128 v50, v[38:41]
	ds_write_b128 v50, v[46:49] offset:32768
	v_add_u32_e32 v50, s48, v111
	s_addc_u32 s1, s45, s1
	ds_write_b128 v50, v[42:45]
	s_waitcnt lgkmcnt(0)
	s_barrier
	v_lshl_add_u32 v214, s57, 7, v1
	v_ashrrev_i32_e32 v215, 31, v214
	v_lshl_add_u64 v[214:215], v[214:215], 2, s[62:63]
	global_load_dword v205, v[214:215], off
	global_load_dword v206, v[214:215], off offset:64
	global_load_dword v207, v[214:215], off offset:128
	global_load_dword v208, v[214:215], off offset:192
	global_load_dword v209, v[214:215], off offset:256
	global_load_dword v210, v[214:215], off offset:320
	global_load_dword v211, v[214:215], off offset:384
	global_load_dword v212, v[214:215], off offset:448
	s_cmpk_lt_i32 s40, 0x200
	s_nop 0
	v_mul_f32_e32 v104, 0x3fb8aa3b, v104
	s_nop 0
	v_mul_f32_e32 v105, 0x3fb8aa3b, v105
	s_nop 0
	v_exp_f32_e32 v104, v104
	v_lshlrev_b32_e32 v50, 2, v1
	v_add_u32_e32 v119, s46, v1
	v_and_b32_e32 v66, 12, v50
	v_bfe_u32 v67, v1, 2, 2
	v_lshlrev_b32_e32 v135, 8, v119
	v_bitop3_b32 v50, v66, v118, v67 bitop3:0x36
	v_add_u32_e32 v52, 4, v118
	v_add_u32_e32 v100, 0, v135
	v_lshlrev_b32_e32 v50, 4, v50
	v_bitop3_b32 v52, v66, v52, v67 bitop3:0x36
	v_add_u32_e32 v51, v100, v50
	v_lshlrev_b32_e32 v72, 4, v52
	v_add_u32_e32 v52, v100, v72
	ds_read_b128 v[58:61], v51
	ds_read_b128 v[54:57], v52
	v_add_u32_e32 v51, 8, v118
	v_lshl_add_u32 v122, v1, 8, 0
	v_bitop3_b32 v51, v66, v51, v67 bitop3:0x36
	v_add_u32_e32 v156, v122, v50
	v_lshlrev_b32_e32 v80, 4, v51
	ds_read_b128 v[50:53], v156 offset:32768
	v_add_u32_e32 v157, v122, v72
	ds_read_b128 v[72:75], v157 offset:32768
	v_add_u32_e32 v62, v100, v80
	ds_read_b128 v[62:65], v62
	s_waitcnt lgkmcnt(2)
	v_mfma_f32_16x16x32_bf16 v[50:53], v[50:53], v[58:61], 0
	v_add_u32_e32 v158, v122, v80
	v_add_u32_e32 v96, 12, v118
	ds_read_b128 v[80:83], v158 offset:32768
	ds_read_b128 v[88:91], v156 offset:36864
	s_waitcnt lgkmcnt(3)
	v_mfma_f32_16x16x32_bf16 v[72:75], v[72:75], v[54:57], v[50:53]
	v_bitop3_b32 v96, v66, v96, v67 bitop3:0x36
	v_lshlrev_b32_e32 v123, 4, v96
	ds_read_b128 v[96:99], v157 offset:36864
	v_add_u32_e32 v50, v100, v123
	v_add_u32_e32 v159, v122, v123
	ds_read_b128 v[50:53], v50
	ds_read_b128 v[100:103], v158 offset:36864
	s_waitcnt lgkmcnt(4)
	v_mfma_f32_16x16x32_bf16 v[72:75], v[80:83], v[62:65], v[72:75]
	ds_read_b128 v[80:83], v159 offset:32768
	ds_read_b128 v[122:125], v159 offset:36864
	s_waitcnt lgkmcnt(1)
	v_mfma_f32_16x16x32_bf16 v[136:139], v[80:83], v[50:53], v[72:75]
	v_mfma_f32_16x16x32_bf16 v[72:75], v[88:91], v[58:61], 0
	v_mfma_f32_16x16x32_bf16 v[72:75], v[96:99], v[54:57], v[72:75]
	v_mfma_f32_16x16x32_bf16 v[72:75], v[100:103], v[62:65], v[72:75]
	s_waitcnt lgkmcnt(0)
	v_mfma_f32_16x16x32_bf16 v[122:125], v[122:125], v[50:53], v[72:75]
	s_nop 5
	ds_read_b128 v[72:75], v156 offset:40960
	ds_read_b128 v[80:83], v156 offset:45056
	ds_read_b128 v[88:91], v157 offset:40960
	ds_read_b128 v[96:99], v157 offset:45056
	s_waitcnt lgkmcnt(3)
	v_mfma_f32_16x16x32_bf16 v[72:75], v[72:75], v[58:61], 0
	s_waitcnt lgkmcnt(1)
	v_mfma_f32_16x16x32_bf16 v[72:75], v[88:91], v[54:57], v[72:75]
	ds_read_b128 v[88:91], v158 offset:40960
	ds_read_b128 v[100:103], v158 offset:45056
	s_waitcnt lgkmcnt(1)
	v_mfma_f32_16x16x32_bf16 v[72:75], v[88:91], v[62:65], v[72:75]
	ds_read_b128 v[88:91], v159 offset:40960
	ds_read_b128 v[140:143], v159 offset:45056
	s_waitcnt lgkmcnt(1)
	v_mfma_f32_16x16x32_bf16 v[144:147], v[88:91], v[50:53], v[72:75]
	v_mfma_f32_16x16x32_bf16 v[72:75], v[80:83], v[58:61], 0
	v_mfma_f32_16x16x32_bf16 v[72:75], v[96:99], v[54:57], v[72:75]
	v_mfma_f32_16x16x32_bf16 v[72:75], v[100:103], v[62:65], v[72:75]
	s_waitcnt lgkmcnt(0)
	v_mfma_f32_16x16x32_bf16 v[100:103], v[140:143], v[50:53], v[72:75]
	s_nop 5
	ds_read_b128 v[72:75], v156 offset:49152
	ds_read_b128 v[80:83], v156 offset:53248
	ds_read_b128 v[88:91], v157 offset:49152
	ds_read_b128 v[140:143], v157 offset:53248
	s_waitcnt lgkmcnt(3)
	v_mfma_f32_16x16x32_bf16 v[72:75], v[72:75], v[58:61], 0
	s_waitcnt lgkmcnt(1)
	v_mfma_f32_16x16x32_bf16 v[72:75], v[88:91], v[54:57], v[72:75]
	ds_read_b128 v[88:91], v158 offset:49152
	ds_read_b128 v[148:151], v158 offset:53248
	s_waitcnt lgkmcnt(1)
	v_mfma_f32_16x16x32_bf16 v[72:75], v[88:91], v[62:65], v[72:75]
	ds_read_b128 v[88:91], v159 offset:49152
	ds_read_b128 v[152:155], v159 offset:53248
	s_waitcnt lgkmcnt(1)
	v_mfma_f32_16x16x32_bf16 v[96:99], v[88:91], v[50:53], v[72:75]
	v_mfma_f32_16x16x32_bf16 v[72:75], v[80:83], v[58:61], 0
	v_mfma_f32_16x16x32_bf16 v[72:75], v[140:143], v[54:57], v[72:75]
	v_mfma_f32_16x16x32_bf16 v[72:75], v[148:151], v[62:65], v[72:75]
	s_waitcnt lgkmcnt(0)
	v_mfma_f32_16x16x32_bf16 v[88:91], v[152:155], v[50:53], v[72:75]
	s_nop 5
	ds_read_b128 v[72:75], v156 offset:57344
	ds_read_b128 v[140:143], v156 offset:61440
	ds_read_b128 v[80:83], v157 offset:57344
	ds_read_b128 v[148:151], v157 offset:61440
	s_waitcnt lgkmcnt(3)
	v_mfma_f32_16x16x32_bf16 v[72:75], v[72:75], v[58:61], 0
	s_waitcnt lgkmcnt(1)
	v_mfma_f32_16x16x32_bf16 v[72:75], v[80:83], v[54:57], v[72:75]
	ds_read_b128 v[80:83], v158 offset:57344
	ds_read_b128 v[152:155], v158 offset:61440
	s_waitcnt lgkmcnt(1)
	v_mfma_f32_16x16x32_bf16 v[72:75], v[80:83], v[62:65], v[72:75]
	ds_read_b128 v[80:83], v159 offset:57344
	ds_read_b128 v[156:159], v159 offset:61440
	s_waitcnt lgkmcnt(1)
	v_mfma_f32_16x16x32_bf16 v[80:83], v[80:83], v[50:53], v[72:75]
	v_mfma_f32_16x16x32_bf16 v[72:75], v[140:143], v[58:61], 0
	v_lshlrev_b32_e32 v142, 2, v118
	v_sub_u32_e32 v143, v119, v142
	v_exp_f32_e32 v140, v105
	v_mfma_f32_16x16x32_bf16 v[72:75], v[148:151], v[54:57], v[72:75]
	v_lshlrev_b32_e32 v141, 3, v118
	v_mul_f32_e32 v105, 0xbfb8aa3b, v104
	v_mul_f32_e32 v104, 0xbfb8aa3b, v140
	v_and_b32_e32 v141, 8, v141
	s_mov_b64 vcc, s[84:85]
	s_cbranch_vccnz .Lp3_maskdone
; __device__ __forceinline__ void ret_phase(const Params& P, LAS unsigned char* lds, int tid, int lane, int wave, int bid, int G) {
;     ...
;             for (int mt = 0; mt < 8; ++mt) {
;                 const f32x4 a = sa[mt];
;                 float e[4];
; #pragma unroll
;                 for (int i = 0; i < 4; ++i) { const int m = 16 * mt + 4 * g + i, df = n - m; const float f = __builtin_amdgcn_exp2f(df >= 0 ? lgf2 * (float)df : lgb2 * (float)(-df)); e[i] = a[i] * f; }
	v_subrev_u32_e32 v213, 0, v143
	v_sub_u32_e32 v218, 0, v143
	v_max_i32_e32 v218, v213, v218
	v_cvt_f32_u32_e32 v218, v218
	v_cmp_gt_i32_e32 vcc, 0, v213
	v_cndmask_b32_e32 v213, v105, v104, vcc
	v_mul_f32_e32 v213, v213, v218
	v_exp_f32_e32 v213, v213
	v_subrev_u32_e32 v219, 1, v143
	v_sub_u32_e32 v218, 1, v143
	v_max_i32_e32 v218, v219, v218
	v_cvt_f32_u32_e32 v218, v218
	v_cmp_gt_i32_e32 vcc, 0, v219
	v_cndmask_b32_e32 v219, v105, v104, vcc
	v_mul_f32_e32 v219, v219, v218
	v_exp_f32_e32 v219, v219
	v_subrev_u32_e32 v220, 2, v143
	v_sub_u32_e32 v218, 2, v143
	v_max_i32_e32 v218, v220, v218
	v_cvt_f32_u32_e32 v218, v218
	v_cmp_gt_i32_e32 vcc, 0, v220
	v_cndmask_b32_e32 v220, v105, v104, vcc
	v_mul_f32_e32 v220, v220, v218
	v_exp_f32_e32 v220, v220
	v_subrev_u32_e32 v221, 3, v143
	v_sub_u32_e32 v218, 3, v143
	v_max_i32_e32 v218, v221, v218
	v_cvt_f32_u32_e32 v218, v218
	v_cmp_gt_i32_e32 vcc, 0, v221
	v_cndmask_b32_e32 v221, v105, v104, vcc
	v_mul_f32_e32 v221, v221, v218
	v_exp_f32_e32 v221, v221
	v_subrev_u32_e32 v222, 16, v143
	v_sub_u32_e32 v218, 16, v143
	v_max_i32_e32 v218, v222, v218
	v_cvt_f32_u32_e32 v218, v218
	v_cmp_gt_i32_e32 vcc, 0, v222
	v_cndmask_b32_e32 v222, v105, v104, vcc
	v_mul_f32_e32 v222, v222, v218
	v_exp_f32_e32 v222, v222
	v_subrev_u32_e32 v223, 17, v143
	v_sub_u32_e32 v218, 17, v143
	v_max_i32_e32 v218, v223, v218
	v_cvt_f32_u32_e32 v218, v218
	v_cmp_gt_i32_e32 vcc, 0, v223
	v_cndmask_b32_e32 v223, v105, v104, vcc
	v_mul_f32_e32 v223, v223, v218
	v_exp_f32_e32 v223, v223
	v_subrev_u32_e32 v224, 18, v143
	v_sub_u32_e32 v218, 18, v143
	v_max_i32_e32 v218, v224, v218
	v_cvt_f32_u32_e32 v218, v218
	v_cmp_gt_i32_e32 vcc, 0, v224
	v_cndmask_b32_e32 v224, v105, v104, vcc
	v_mul_f32_e32 v224, v224, v218
	v_exp_f32_e32 v224, v224
	v_subrev_u32_e32 v225, 19, v143
	v_sub_u32_e32 v218, 19, v143
	v_max_i32_e32 v218, v225, v218
	v_cvt_f32_u32_e32 v218, v218
	v_cmp_gt_i32_e32 vcc, 0, v225
	v_cndmask_b32_e32 v225, v105, v104, vcc
	v_mul_f32_e32 v225, v225, v218
	v_exp_f32_e32 v225, v225
	v_subrev_u32_e32 v226, 32, v143
	v_sub_u32_e32 v218, 32, v143
	v_max_i32_e32 v218, v226, v218
	v_cvt_f32_u32_e32 v218, v218
	v_cmp_gt_i32_e32 vcc, 0, v226
	v_cndmask_b32_e32 v226, v105, v104, vcc
	v_mul_f32_e32 v226, v226, v218
	v_exp_f32_e32 v226, v226
	v_subrev_u32_e32 v227, 33, v143
	v_sub_u32_e32 v218, 33, v143
	v_max_i32_e32 v218, v227, v218
	v_cvt_f32_u32_e32 v218, v218
	v_cmp_gt_i32_e32 vcc, 0, v227
	v_cndmask_b32_e32 v227, v105, v104, vcc
	v_mul_f32_e32 v227, v227, v218
	v_exp_f32_e32 v227, v227
	v_subrev_u32_e32 v228, 34, v143
	v_sub_u32_e32 v218, 34, v143
	v_max_i32_e32 v218, v228, v218
	v_cvt_f32_u32_e32 v218, v218
	v_cmp_gt_i32_e32 vcc, 0, v228
	v_cndmask_b32_e32 v228, v105, v104, vcc
	v_mul_f32_e32 v228, v228, v218
	v_exp_f32_e32 v228, v228
	v_subrev_u32_e32 v229, 35, v143
	v_sub_u32_e32 v218, 35, v143
	v_max_i32_e32 v218, v229, v218
	v_cvt_f32_u32_e32 v218, v218
	v_cmp_gt_i32_e32 vcc, 0, v229
	v_cndmask_b32_e32 v229, v105, v104, vcc
	v_mul_f32_e32 v229, v229, v218
	v_exp_f32_e32 v229, v229
	v_subrev_u32_e32 v230, 48, v143
	v_sub_u32_e32 v218, 48, v143
	v_max_i32_e32 v218, v230, v218
	v_cvt_f32_u32_e32 v218, v218
	v_cmp_gt_i32_e32 vcc, 0, v230
	v_cndmask_b32_e32 v230, v105, v104, vcc
	v_mul_f32_e32 v230, v230, v218
	v_exp_f32_e32 v230, v230
	v_subrev_u32_e32 v231, 49, v143
	v_sub_u32_e32 v218, 49, v143
	v_max_i32_e32 v218, v231, v218
	v_cvt_f32_u32_e32 v218, v218
	v_cmp_gt_i32_e32 vcc, 0, v231
	v_cndmask_b32_e32 v231, v105, v104, vcc
	v_mul_f32_e32 v231, v231, v218
	v_exp_f32_e32 v231, v231
	v_subrev_u32_e32 v232, 50, v143
	v_sub_u32_e32 v218, 50, v143
	v_max_i32_e32 v218, v232, v218
	v_cvt_f32_u32_e32 v218, v218
	v_cmp_gt_i32_e32 vcc, 0, v232
	v_cndmask_b32_e32 v232, v105, v104, vcc
	v_mul_f32_e32 v232, v232, v218
	v_exp_f32_e32 v232, v232
	v_subrev_u32_e32 v233, 51, v143
	v_sub_u32_e32 v218, 51, v143
	v_max_i32_e32 v218, v233, v218
	v_cvt_f32_u32_e32 v218, v218
	v_cmp_gt_i32_e32 vcc, 0, v233
	v_cndmask_b32_e32 v233, v105, v104, vcc
	v_mul_f32_e32 v233, v233, v218
	v_exp_f32_e32 v233, v233
	v_subrev_u32_e32 v234, 64, v143
; __device__ __forceinline__ void ret_phase(const Params& P, LAS unsigned char* lds, int tid, int lane, int wave, int bid, int G) {
;     ...
;             for (int mt = 0; mt < 8; ++mt) {
;                 const f32x4 a = sa[mt];
;                 float e[4];
; #pragma unroll
;                 for (int i = 0; i < 4; ++i) { const int m = 16 * mt + 4 * g + i, df = n - m; const float f = __builtin_amdgcn_exp2f(df >= 0 ? lgf2 * (float)df : lgb2 * (float)(-df)); e[i] = a[i] * f; }
	v_sub_u32_e32 v218, 64, v143
	v_max_i32_e32 v218, v234, v218
	v_cvt_f32_u32_e32 v218, v218
	v_cmp_gt_i32_e32 vcc, 0, v234
	v_cndmask_b32_e32 v234, v105, v104, vcc
	v_mul_f32_e32 v234, v234, v218
	v_exp_f32_e32 v234, v234
	v_subrev_u32_e32 v235, 65, v143
	v_sub_u32_e32 v218, 65, v143
	v_max_i32_e32 v218, v235, v218
	v_cvt_f32_u32_e32 v218, v218
	v_cmp_gt_i32_e32 vcc, 0, v235
	v_cndmask_b32_e32 v235, v105, v104, vcc
	v_mul_f32_e32 v235, v235, v218
	v_exp_f32_e32 v235, v235
	v_subrev_u32_e32 v236, 66, v143
	v_sub_u32_e32 v218, 66, v143
	v_max_i32_e32 v218, v236, v218
	v_cvt_f32_u32_e32 v218, v218
	v_cmp_gt_i32_e32 vcc, 0, v236
	v_cndmask_b32_e32 v236, v105, v104, vcc
	v_mul_f32_e32 v236, v236, v218
	v_exp_f32_e32 v236, v236
	v_subrev_u32_e32 v237, 67, v143
	v_sub_u32_e32 v218, 67, v143
	v_max_i32_e32 v218, v237, v218
	v_cvt_f32_u32_e32 v218, v218
	v_cmp_gt_i32_e32 vcc, 0, v237
	v_cndmask_b32_e32 v237, v105, v104, vcc
	v_mul_f32_e32 v237, v237, v218
	v_exp_f32_e32 v237, v237
	v_subrev_u32_e32 v238, 80, v143
	v_sub_u32_e32 v218, 80, v143
	v_max_i32_e32 v218, v238, v218
	v_cvt_f32_u32_e32 v218, v218
	v_cmp_gt_i32_e32 vcc, 0, v238
	v_cndmask_b32_e32 v238, v105, v104, vcc
	v_mul_f32_e32 v238, v238, v218
	v_exp_f32_e32 v238, v238
	v_subrev_u32_e32 v239, 81, v143
	v_sub_u32_e32 v218, 81, v143
	v_max_i32_e32 v218, v239, v218
	v_cvt_f32_u32_e32 v218, v218
	v_cmp_gt_i32_e32 vcc, 0, v239
	v_cndmask_b32_e32 v239, v105, v104, vcc
	v_mul_f32_e32 v239, v239, v218
	v_exp_f32_e32 v239, v239
	v_subrev_u32_e32 v240, 82, v143
	v_sub_u32_e32 v218, 82, v143
	v_max_i32_e32 v218, v240, v218
	v_cvt_f32_u32_e32 v218, v218
	v_cmp_gt_i32_e32 vcc, 0, v240
	v_cndmask_b32_e32 v240, v105, v104, vcc
	v_mul_f32_e32 v240, v240, v218
	v_exp_f32_e32 v240, v240
	v_subrev_u32_e32 v241, 83, v143
	v_sub_u32_e32 v218, 83, v143
	v_max_i32_e32 v218, v241, v218
	v_cvt_f32_u32_e32 v218, v218
	v_cmp_gt_i32_e32 vcc, 0, v241
	v_cndmask_b32_e32 v241, v105, v104, vcc
	v_mul_f32_e32 v241, v241, v218
	v_exp_f32_e32 v241, v241
	v_subrev_u32_e32 v242, 96, v143
	v_sub_u32_e32 v218, 96, v143
	v_max_i32_e32 v218, v242, v218
	v_cvt_f32_u32_e32 v218, v218
	v_cmp_gt_i32_e32 vcc, 0, v242
	v_cndmask_b32_e32 v242, v105, v104, vcc
	v_mul_f32_e32 v242, v242, v218
	v_exp_f32_e32 v242, v242
	v_subrev_u32_e32 v243, 97, v143
	v_sub_u32_e32 v218, 97, v143
	v_max_i32_e32 v218, v243, v218
	v_cvt_f32_u32_e32 v218, v218
	v_cmp_gt_i32_e32 vcc, 0, v243
	v_cndmask_b32_e32 v243, v105, v104, vcc
	v_mul_f32_e32 v243, v243, v218
	v_exp_f32_e32 v243, v243
	v_subrev_u32_e32 v244, 98, v143
	v_sub_u32_e32 v218, 98, v143
	v_max_i32_e32 v218, v244, v218
	v_cvt_f32_u32_e32 v218, v218
	v_cmp_gt_i32_e32 vcc, 0, v244
	v_cndmask_b32_e32 v244, v105, v104, vcc
	v_mul_f32_e32 v244, v244, v218
	v_exp_f32_e32 v244, v244
	v_subrev_u32_e32 v245, 99, v143
	v_sub_u32_e32 v218, 99, v143
	v_max_i32_e32 v218, v245, v218
	v_cvt_f32_u32_e32 v218, v218
	v_cmp_gt_i32_e32 vcc, 0, v245
	v_cndmask_b32_e32 v245, v105, v104, vcc
	v_mul_f32_e32 v245, v245, v218
	v_exp_f32_e32 v245, v245
	v_subrev_u32_e32 v246, 112, v143
	v_sub_u32_e32 v218, 112, v143
	v_max_i32_e32 v218, v246, v218
	v_cvt_f32_u32_e32 v218, v218
	v_cmp_gt_i32_e32 vcc, 0, v246
	v_cndmask_b32_e32 v246, v105, v104, vcc
	v_mul_f32_e32 v246, v246, v218
	v_exp_f32_e32 v246, v246
	v_subrev_u32_e32 v247, 113, v143
	v_sub_u32_e32 v218, 113, v143
	v_max_i32_e32 v218, v247, v218
	v_cvt_f32_u32_e32 v218, v218
	v_cmp_gt_i32_e32 vcc, 0, v247
	v_cndmask_b32_e32 v247, v105, v104, vcc
	v_mul_f32_e32 v247, v247, v218
	v_exp_f32_e32 v247, v247
	v_subrev_u32_e32 v248, 114, v143
	v_sub_u32_e32 v218, 114, v143
	v_max_i32_e32 v218, v248, v218
	v_cvt_f32_u32_e32 v218, v218
	v_cmp_gt_i32_e32 vcc, 0, v248
	v_cndmask_b32_e32 v248, v105, v104, vcc
	v_mul_f32_e32 v248, v248, v218
	v_exp_f32_e32 v248, v248
	v_subrev_u32_e32 v249, 115, v143
	v_sub_u32_e32 v218, 115, v143
	v_max_i32_e32 v218, v249, v218
	v_cvt_f32_u32_e32 v218, v218
	v_cmp_gt_i32_e32 vcc, 0, v249
	v_cndmask_b32_e32 v249, v105, v104, vcc
	v_mul_f32_e32 v249, v249, v218
	v_exp_f32_e32 v249, v249
	s_mov_b64 s[84:85], s[86:87]

; __global__ void __launch_bounds__(512, 2) mk_fwd(Params P, int ph_lo, int ph_hi) {
	.amdhsa_kernel _Z6mk_fwd6Paramsii
		.amdhsa_group_segment_fixed_size 0
		.amdhsa_private_segment_fixed_size 0
		.amdhsa_kernarg_size 400
		.amdhsa_user_sgpr_count 2
		.amdhsa_user_sgpr_dispatch_ptr 0
		.amdhsa_user_sgpr_queue_ptr 0
		.amdhsa_user_sgpr_kernarg_segment_ptr 1
		.amdhsa_user_sgpr_dispatch_id 0
		.amdhsa_user_sgpr_kernarg_preload_length 0
		.amdhsa_user_sgpr_kernarg_preload_offset 0
		.amdhsa_user_sgpr_private_segment_size 0
		.amdhsa_uses_dynamic_stack 0
		.amdhsa_enable_private_segment 0
		.amdhsa_system_sgpr_workgroup_id_x 1
		.amdhsa_system_sgpr_workgroup_id_y 0
		.amdhsa_system_sgpr_workgroup_id_z 0
		.amdhsa_system_sgpr_workgroup_info 0
		.amdhsa_system_vgpr_workitem_id 0
		.amdhsa_next_free_vgpr 256
		.amdhsa_next_free_sgpr 100
		.amdhsa_accum_offset 256
		.amdhsa_reserve_vcc 1
		.amdhsa_float_round_mode_32 0
		.amdhsa_float_round_mode_16_64 0
		.amdhsa_float_denorm_mode_32 3
		.amdhsa_float_denorm_mode_16_64 3
		.amdhsa_dx10_clamp 1
		.amdhsa_ieee_mode 1
		.amdhsa_fp16_overflow 0
		.amdhsa_tg_split 0
		.amdhsa_exception_fp_ieee_invalid_op 0
		.amdhsa_exception_fp_denorm_src 0
		.amdhsa_exception_fp_ieee_div_zero 0
		.amdhsa_exception_fp_ieee_overflow 0
		.amdhsa_exception_fp_ieee_underflow 0
		.amdhsa_exception_fp_ieee_inexact 0
		.amdhsa_exception_int_div_zero 0
	.end_amdhsa_kernel

; #define LAS __attribute__((address_space(3)))
; __global__ void __launch_bounds__(512, 2) mk_fwd(Params P, int ph_lo, int ph_hi) {
;     extern __shared__ __attribute__((aligned(16))) unsigned char lds_raw[];
;     LAS unsigned char* lds = (LAS unsigned char*)lds_raw;
;     const int tid = threadIdx.x, lane = tid & 63, wave = __builtin_amdgcn_readfirstlane(tid >> 6), bid = blockIdx.x, G = gridDim.x;
amdhsa.kernels:
  - .agpr_count:     0
    .args:
      - .offset:         0
        .size:           136
        .value_kind:     by_value
      - .offset:         136
        .size:           4
        .value_kind:     by_value
      - .offset:         140
        .size:           4
        .value_kind:     by_value
      - .offset:         144
        .size:           4
        .value_kind:     hidden_block_count_x
      - .offset:         148
        .size:           4
        .value_kind:     hidden_block_count_y
      - .offset:         152
        .size:           4
        .value_kind:     hidden_block_count_z
      - .offset:         156
        .size:           2
        .value_kind:     hidden_group_size_x
      - .offset:         158
        .size:           2
        .value_kind:     hidden_group_size_y
      - .offset:         160
        .size:           2
        .value_kind:     hidden_group_size_z
      - .offset:         162
        .size:           2
        .value_kind:     hidden_remainder_x
      - .offset:         164
        .size:           2
        .value_kind:     hidden_remainder_y
      - .offset:         166
        .size:           2
        .value_kind:     hidden_remainder_z
      - .offset:         184
        .size:           8
        .value_kind:     hidden_global_offset_x
      - .offset:         192
        .size:           8
        .value_kind:     hidden_global_offset_y
      - .offset:         200
        .size:           8
        .value_kind:     hidden_global_offset_z
      - .offset:         208
        .size:           2
        .value_kind:     hidden_grid_dims
      - .offset:         264
        .size:           4
        .value_kind:     hidden_dynamic_lds_size
    .group_segment_fixed_size: 0
    .kernarg_segment_align: 8
    .kernarg_segment_size: 400
    .language:       OpenCL C
    .language_version:
      - 2
      - 0
    .max_flat_workgroup_size: 512
    .name:           _Z6mk_fwd6Paramsii
    .private_segment_fixed_size: 0
    .sgpr_count:     106
    .sgpr_spill_count: 4
    .symbol:         _Z6mk_fwd6Paramsii.kd
    .uniform_work_group_size: 1
    .uses_dynamic_stack: false
    .vgpr_count:     256
    .vgpr_spill_count: 0
    .wavefront_size: 64
